# G1 grouped half-sweeps (4 tokens per group) with priority held high through the whole gather phases, low in selection
# speedup vs baseline: 1.0058x; 1.0058x over previous
.Lg1_tok:
	s_mul_i32 s71, s95, s33
	s_add_u32 s71, s71, s94
	s_cmp_ge_u32 s71, s46
	s_cbranch_scc1 .Lg1_phase_done
	v_mov_b32_e32 v116, s71
	s_mul_i32 s97, s95, 2560
	s_cmp_lg_u32 s96, 0
	s_cbranch_scc1 .Lg1_rdisp
	v_add_u32_e32 v189, s97, v127
	s_setprio 0
	s_branch .LBB0_978
.Lg1_rdisp:
	s_setprio 1
	v_add_u32_e32 v226, s97, v135
	s_add_u32 s32, s71, s33
	s_add_u32 s97, s95, 1
	s_cmp_lt_u32 s97, 4
	s_cselect_b32 s97, 1, 0
	s_cmp_lt_u32 s32, s46
	s_cselect_b32 s71, 1, 0
	s_and_b32 s97, s97, s71
	s_mul_i32 s71, s33, 4
	s_add_u32 s71, s71, s94
	s_cmp_lt_u32 s71, s46
	s_cselect_b32 s71, s71, s94
	s_cmp_eq_u32 s96, 1
	s_cselect_b32 s71, s94, s71
	s_cmp_lg_u32 s97, 0
	s_cselect_b32 s71, s32, s71
	v_mov_b32_e32 v227, s71
	s_mul_i32 s97, s95, 2560
	s_ff1_i32_b32 s32, s33
	s_add_u32 s32, s32, 2
	s_lshr_b32 s32, s94, s32
	s_add_u32 s71, s96, -1
	s_xor_b32 s32, s32, s71
	s_and_b32 s32, s32, 1
	s_lshl_b32 s71, s32, 8
	s_add_u32 s97, s97, s71
	s_lshl_b32 s71, s32, 6
	s_add_u32 s71, s71, 0x1f
	s_lshl_b32 s32, s32, 6
	s_add_u32 s32, s32, 0xffffffe0
	s_branch .Lg1_rtok

.LBB0_977:
	s_cmp_lg_u32 s96, 2
	s_cbranch_scc1 .Lg1_tok_next
	s_mul_i32 s97, s95, 2560
	v_add_u32_e32 v6, s97, v135
	s_waitcnt lgkmcnt(0)
	ds_read2st64_b64 v[0:3], v6 offset0:6 offset1:8
	v_lshlrev_b64 v[4:5], 9, v[116:117]
	v_mov_b32_e32 v116, v141
	s_waitcnt lgkmcnt(0)
	v_fma_mixlo_f16 v2, v2, s62, 0
	v_fma_mixhi_f16 v3, v3, s62, 0
	v_lshl_or_b32 v0, v2, 16, v0
	v_and_or_b32 v1, v3, s50, v1
	v_lshl_add_u64 v[2:3], v[122:123], 0, v[4:5]
	global_store_dwordx2 v[2:3], v[0:1], off
	s_waitcnt lgkmcnt(0)
	s_branch .Lg1_tok_next
